# attention PV tail: the two wait states before v_permlane32_swap now carry the two independent row-sum adds instead of s_nop 1
# baseline (speedup 1.0000x reference)
.LBB0_1051:
	v_pk_add_f32 v[208:209], v[64:65], v[166:167] op_sel:[0,1] op_sel_hi:[1,1] neg_lo:[0,1] neg_hi:[0,1]
	v_pk_add_f32 v[210:211], v[66:67], v[166:167] op_sel:[0,1] op_sel_hi:[1,1] neg_lo:[0,1] neg_hi:[0,1]
	v_pk_add_f32 v[212:213], v[68:69], v[166:167] op_sel:[0,1] op_sel_hi:[1,1] neg_lo:[0,1] neg_hi:[0,1]
	v_pk_add_f32 v[214:215], v[70:71], v[166:167] op_sel:[0,1] op_sel_hi:[1,1] neg_lo:[0,1] neg_hi:[0,1]
	v_pk_add_f32 v[216:217], v[72:73], v[166:167] op_sel:[0,1] op_sel_hi:[1,1] neg_lo:[0,1] neg_hi:[0,1]
	v_pk_add_f32 v[218:219], v[74:75], v[166:167] op_sel:[0,1] op_sel_hi:[1,1] neg_lo:[0,1] neg_hi:[0,1]
	v_pk_add_f32 v[220:221], v[76:77], v[166:167] op_sel:[0,1] op_sel_hi:[1,1] neg_lo:[0,1] neg_hi:[0,1]
	v_pk_add_f32 v[222:223], v[78:79], v[166:167] op_sel:[0,1] op_sel_hi:[1,1] neg_lo:[0,1] neg_hi:[0,1]
	v_exp_f32_e32 v190, v208
	ds_read2_b64 v[64:67], v201 offset0:128 offset1:130
	v_exp_f32_e32 v191, v209
	v_exp_f32_e32 v192, v210
	v_exp_f32_e32 v193, v211
	v_exp_f32_e32 v194, v212
	v_cvt_pk_bf16_f32 v70, v92, v93
	v_exp_f32_e32 v195, v213
	v_exp_f32_e32 v92, v214
	v_exp_f32_e32 v93, v215
	v_cvt_pk_bf16_f32 v68, v88, v89
	v_cvt_pk_bf16_f32 v69, v90, v91
	v_cvt_pk_bf16_f32 v71, v94, v95
	v_cvt_pk_bf16_f32 v88, v190, v191
	v_cvt_pk_bf16_f32 v89, v192, v193
	v_cvt_pk_bf16_f32 v90, v194, v195
	v_cvt_pk_bf16_f32 v91, v92, v93
	s_waitcnt lgkmcnt(0)
	v_mfma_f32_32x32x16_bf16 v[48:63], v[64:67], v[68:71], v[48:63]
	v_exp_f32_e32 v196, v218
	v_mfma_f32_32x32x16_bf16 v[16:31], v[64:67], v[88:91], v[16:31]
	ds_read2_b64 v[64:67], v202 offset0:160 offset1:162
	v_exp_f32_e32 v197, v219
	v_exp_f32_e32 v74, v220
	v_exp_f32_e32 v75, v221
	s_waitcnt lgkmcnt(0)
	v_mfma_f32_32x32x16_bf16 v[32:47], v[64:67], v[68:71], v[32:47]
	v_exp_f32_e32 v94, v216
	v_exp_f32_e32 v95, v217
	ds_read2_b64 v[68:71], v201 offset0:132 offset1:134
	v_cvt_pk_bf16_f32 v73, v196, v197
	v_cvt_pk_bf16_f32 v72, v94, v95
	v_mfma_f32_32x32x16_bf16 v[0:15], v[64:67], v[88:91], v[0:15]
	v_exp_f32_e32 v88, v222
	v_exp_f32_e32 v89, v223
	ds_read2_b64 v[76:79], v202 offset0:164 offset1:166
	v_cvt_pk_bf16_f32 v64, v80, v81
	v_cvt_pk_bf16_f32 v65, v82, v83
	v_cvt_pk_bf16_f32 v66, v84, v85
	v_cvt_pk_bf16_f32 v67, v86, v87
	v_pk_add_f32 v[80:81], v[194:195], v[74:75]
	v_cvt_pk_bf16_f32 v74, v74, v75
	v_cvt_pk_bf16_f32 v75, v88, v89
	s_waitcnt lgkmcnt(1)
	v_mfma_f32_32x32x16_bf16 v[48:63], v[68:71], v[64:67], v[48:63]
	v_add_f32_e64 v82, v192, v196
	v_add_f32_e64 v83, v193, v197
	v_mfma_f32_32x32x16_bf16 v[16:31], v[68:71], v[72:75], v[16:31]
	v_add_f32_e64 v68, v190, v94
	v_add_f32_e64 v69, v191, v95
	v_add_f32_e64 v70, v92, v88
	v_add_f32_e64 v71, v93, v89
	v_add_f32_e64 v68, v68, v80
	v_add_f32_e64 v69, v69, v81
	v_pk_add_f32 v[70:71], v[82:83], v[70:71]
	s_nop 0
	v_pk_add_f32 v[68:69], v[68:69], v[70:71]
	s_nop 0
	v_add_f32_e32 v68, v68, v69
	s_waitcnt lgkmcnt(0)
	v_mfma_f32_32x32x16_bf16 v[32:47], v[76:79], v[64:67], v[32:47]
	v_mov_b32_e32 v64, v68
	v_add_f32_e32 v65, v188, v189
	v_add_f32_e32 v162, v162, v65
	v_permlane32_swap_b32_e32 v64, v68
	s_waitcnt lgkmcnt(0)
	v_add_f32_e32 v64, v68, v64
	v_add_f32_e32 v160, v160, v64
	v_mfma_f32_32x32x16_bf16 v[0:15], v[76:79], v[72:75], v[0:15]
